# P7->P8 seam: cooperative-groups grid.sync skipped (XCD barrier kept); GLA chunk-local unit: gate-weight loads issued with the other unit-start loads before one wait
# speedup vs baseline: 1.0518x; 1.0028x over previous
; #define LAS __attribute__((address_space(3)))
; __device__ __forceinline__ void gla_a_unit(LAS unsigned char* lds, bf16* QKA, bf16* VA, const float* FA, unsigned char* ws, int xnrow0, float* DECB, int lchunk, int h,
;                                            const float* wgate, const float* bgate, int tid) {
;     ...
;     u32x4 qv[2], kv[2];
; #pragma unroll
;     for (int i = 0; i < 2; ++i) { const int id = tid + 512 * i, row = id >> 4, ch = id & 15; const bf16* p = QKA + (row0 + row) * 1024 + h * 128 + ch * 8; qv[i] = *(const u32x4*)p; kv[i] = *(const u32x4*)(p + 512); }
;     if (tid < 256) *(LAS f32x4*)(FAi + tid * 4) = *(const f32x4*)(FA + row0 * 16 + tid * 4);
; #pragma unroll
;     for (int i = 0; i < 4; ++i) { const int id = tid + 512 * i, row = id >> 5, ch = id & 31; *(LAS u32x4*)(lds + G_VV + row * GVP + ch * 16) = *(const u32x4*)(VA + (row0 + row) * 1024 + h * 256 + ch * 8); }
;     __syncthreads();
;     {
;         float wg[16];
; #pragma unroll
;         for (int r = 0; r < 16; ++r) wg[r] = wgate[r * 512 + h * 128 + gd];
;         const float bg = bgate[h * 128 + gd];
;         float run = 0.f;
; #pragma unroll
;         for (int tt = 0; tt < 16; ++tt) { const int t = tq * 16 + tt; const LAS f32x4* fp = (const LAS f32x4*)(FAi + t * 16); float x = bg;
; #pragma unroll
;             for (int q = 0; q < 4; ++q) { const f32x4 f = fp[q]; x += f[0] * wg[4 * q] + f[1] * wg[4 * q + 1] + f[2] * wg[4 * q + 2] + f[3] * wg[4 * q + 3]; }
;             const float ls = fminf(x, 0.f) - __logf(1.0f + __expf(-fabsf(x))); run += ls * 0.0625f; Bimg[t * GBP + gd] = run;
.LBB0_558:
	s_mov_b32 s0, s66
	s_ashr_i32 s66, s3, 2
	s_mov_b32 s33, s67
	s_ashr_i32 s67, s66, 31
	s_and_b32 s97, s3, 3
	s_lshl_b64 s[82:83], s[66:67], 6
	s_lshl_b32 s78, s97, 8
	v_lshl_add_u64 v[6:7], s[82:83], 0, v[100:101]
	v_lshl_add_u64 v[4:5], v[118:119], 0, s[78:79]
	v_lshlrev_b64 v[6:7], 11, v[6:7]
	v_lshl_add_u64 v[62:63], v[4:5], 0, v[6:7]
	v_lshl_add_u64 v[6:7], s[82:83], 0, v[102:103]
	v_lshlrev_b64 v[6:7], 11, v[6:7]
	s_mov_b64 s[6:7], s[90:91]
	v_lshl_add_u64 v[60:61], v[4:5], 0, v[6:7]
	s_mov_b32 s69, s64
	s_mov_b32 s68, s70
	s_load_dwordx2 s[62:63], s[6:7], 0x50
	s_mov_b64 s[70:71], s[90:91]
	s_load_dwordx2 s[64:65], s[90:91], 0x58
	global_load_dwordx4 v[16:19], v[62:63], off
	global_load_dwordx4 v[12:15], v[62:63], off offset:1024
	global_load_dwordx4 v[8:11], v[60:61], off
	global_load_dwordx4 v[4:7], v[60:61], off offset:1024
	v_readfirstlane_b32 s2, v117
	s_lshl_b32 s96, s97, 7
	s_lshl_b32 s6, s97, 9
	s_mov_b32 s7, s79
	v_lshl_add_u64 v[24:25], v[106:107], 0, s[6:7]
	v_lshl_add_u64 v[20:21], s[82:83], 0, v[108:109]
	v_lshlrev_b64 v[20:21], 11, v[20:21]
	v_lshl_add_u64 v[20:21], v[24:25], 0, v[20:21]
	global_load_dwordx4 v[44:47], v[20:21], off
	v_lshl_add_u64 v[20:21], s[82:83], 0, v[110:111]
	v_lshlrev_b64 v[20:21], 11, v[20:21]
	v_lshl_add_u64 v[20:21], v[24:25], 0, v[20:21]
	global_load_dwordx4 v[48:51], v[20:21], off
	v_lshl_add_u64 v[20:21], s[82:83], 0, v[112:113]
	v_lshlrev_b64 v[20:21], 11, v[20:21]
	v_lshl_add_u64 v[20:21], v[24:25], 0, v[20:21]
	global_load_dwordx4 v[52:55], v[20:21], off
	v_lshl_add_u64 v[20:21], s[82:83], 0, v[114:115]
	v_lshlrev_b64 v[20:21], 11, v[20:21]
	v_lshl_add_u64 v[20:21], v[24:25], 0, v[20:21]
	global_load_dwordx4 v[56:59], v[20:21], off
	s_and_saveexec_b64 s[6:7], vcc
	s_cbranch_execz .LBB0_560
	s_lshl_b64 s[66:67], s[66:67], 12
	v_lshl_add_u64 v[20:21], v[104:105], 0, s[66:67]
	global_load_dwordx4 v[20:23], v[20:21], off
	s_waitcnt vmcnt(0)
	ds_write_b128 v127, v[20:23]
.LBB0_560:
	s_or_b64 exec, exec, s[6:7]
	s_lshl_b32 s6, s97, 9
	s_mov_b32 s7, s79
	v_or_b32_e32 v2, s96, v126
	v_lshlrev_b32_e32 v2, 2, v2
	s_waitcnt lgkmcnt(0)
	v_lshl_add_u64 v[34:35], s[62:63], 0, v[2:3]
	s_movk_i32 s97, 0x1000
	s_movk_i32 s96, 0x2000
	s_movk_i32 s6, 0x3000
	global_load_dword v20, v2, s[62:63]
	global_load_dword v22, v2, s[62:63] offset:2048
	v_add_co_u32_e64 v26, s[62:63], s97, v34
	s_nop 1
	v_addc_co_u32_e64 v27, s[62:63], 0, v35, s[62:63]
	v_add_co_u32_e64 v28, s[62:63], s96, v34
	s_nop 1
	v_addc_co_u32_e64 v29, s[62:63], 0, v35, s[62:63]
	global_load_dword v25, v[28:29], off offset:-4096
	global_load_dword v23, v[26:27], off offset:2048
	global_load_dword v21, v[28:29], off
	global_load_dword v24, v[28:29], off offset:2048
	v_add_co_u32_e64 v26, s[62:63], s6, v34
	s_movk_i32 s6, 0x4000
	s_nop 0
	v_addc_co_u32_e64 v27, s[62:63], 0, v35, s[62:63]
	v_add_co_u32_e64 v30, s[62:63], s6, v34
	s_movk_i32 s6, 0x5000
	s_nop 0
	v_addc_co_u32_e64 v31, s[62:63], 0, v35, s[62:63]
	global_load_dword v29, v[30:31], off offset:-4096
	s_nop 0
	global_load_dword v27, v[26:27], off offset:2048
	s_nop 0
	global_load_dword v26, v[30:31], off
	global_load_dword v28, v[30:31], off offset:2048
	v_add_co_u32_e64 v30, s[62:63], s6, v34
	s_movk_i32 s6, 0x6000
	s_nop 0
	v_addc_co_u32_e64 v31, s[62:63], 0, v35, s[62:63]
	v_add_co_u32_e64 v36, s[62:63], s6, v34
	s_movk_i32 s6, 0x7000
	s_nop 0
	v_addc_co_u32_e64 v37, s[62:63], 0, v35, s[62:63]
	global_load_dword v33, v[36:37], off offset:-4096
	s_nop 0
	global_load_dword v31, v[30:31], off offset:2048
	s_nop 0
	global_load_dword v30, v[36:37], off
	global_load_dword v32, v[36:37], off offset:2048
	v_add_co_u32_e64 v36, s[62:63], s6, v34
	v_readlane_b32 s6, v251, 53
	s_nop 0
	v_addc_co_u32_e64 v37, s[62:63], 0, v35, s[62:63]
	global_load_dword v34, v[36:37], off
	global_load_dword v35, v[36:37], off offset:2048
	s_nop 0
	global_load_dword v2, v2, s[64:65]
	s_waitcnt vmcnt(0)
	ds_write_b128 v134, v[44:47] offset:34816
	ds_write_b128 v135, v[48:51] offset:34816
	ds_write_b128 v136, v[52:55] offset:34816
	ds_write_b128 v137, v[56:59] offset:34816
	s_waitcnt lgkmcnt(0)
	s_barrier
	v_add_u32_e32 v48, s6, v128
	ds_read_b128 v[36:39], v48
	ds_read_b128 v[40:43], v48 offset:16
	ds_read_b128 v[44:47], v48 offset:32
	ds_read_b128 v[48:51], v48 offset:48
	s_mov_b32 s6, 0x3d800000
	s_waitcnt vmcnt(15) lgkmcnt(3)
	v_mul_f32_e32 v37, v22, v37
	v_fmac_f32_e32 v37, v20, v36
	s_waitcnt vmcnt(14)
	v_fmac_f32_e32 v37, v25, v38
	s_waitcnt vmcnt(13)
	v_fmac_f32_e32 v37, v23, v39
	s_waitcnt vmcnt(0)
	v_add_f32_e32 v36, v2, v37
	s_waitcnt lgkmcnt(2)
	v_mul_f32_e32 v37, v24, v41
	v_fmac_f32_e32 v37, v21, v40
	v_fmac_f32_e32 v37, v29, v42
	v_fmac_f32_e32 v37, v27, v43
	v_add_f32_e32 v36, v36, v37
	s_waitcnt lgkmcnt(1)
	v_mul_f32_e32 v37, v28, v45
	v_fmac_f32_e32 v37, v26, v44
	v_fmac_f32_e32 v37, v33, v46
	v_fmac_f32_e32 v37, v31, v47
	v_add_f32_e32 v36, v36, v37
	s_waitcnt lgkmcnt(0)
	v_mul_f32_e32 v37, v32, v49
	v_fmac_f32_e32 v37, v30, v48
	v_fmac_f32_e32 v37, v34, v50
	v_fmac_f32_e32 v37, v35, v51
	v_add_f32_e32 v36, v36, v37
	v_min_f32_e32 v37, 0, v36
	v_mul_f32_e64 v36, |v36|, s93
	v_exp_f32_e32 v36, v36
	s_nop 0
	v_add_f32_e32 v36, 1.0, v36
	v_cmp_gt_f32_e64 s[62:63], s92, v36
	s_nop 1
	v_cndmask_b32_e64 v38, 0, 32, s[62:63]
	v_ldexp_f32 v36, v36, v38
	v_log_f32_e32 v36, v36
	s_nop 0
	v_mul_f32_e32 v38, 0x3f317217, v36
	v_fma_f32 v38, v36, s1, -v38
	v_fmac_f32_e32 v38, 0x3377d1cf, v36
	v_fmac_f32_e32 v38, 0x3f317217, v36
	v_cmp_lt_f32_e64 s[64:65], |v36|, s72
	s_nop 1
	v_cndmask_b32_e64 v36, v36, v38, s[64:65]
	v_cndmask_b32_e64 v38, 0, v208, s[62:63]
	v_sub_f32_e32 v36, v36, v38
	v_sub_f32_e32 v36, v37, v36
	v_fma_f32 v36, v36, s6, 0
	ds_write_b32 v138, v36
	ds_read_b128 v[38:41], v154
	ds_read_b128 v[42:45], v154 offset:16
	ds_read_b128 v[46:49], v154 offset:32
	ds_read_b128 v[50:53], v154 offset:48
	s_mov_b64 s[6:7], 0x4200000
	s_waitcnt lgkmcnt(3)
; #define LAS __attribute__((address_space(3)))
; __device__ __forceinline__ void gla_a_unit(LAS unsigned char* lds, bf16* QKA, bf16* VA, const float* FA, unsigned char* ws, int xnrow0, float* DECB, int lchunk, int h,
;                                            const float* wgate, const float* bgate, int tid) {
;     ...
;         float run = 0.f;
; #pragma unroll
;         for (int tt = 0; tt < 16; ++tt) { const int t = tq * 16 + tt; const LAS f32x4* fp = (const LAS f32x4*)(FAi + t * 16); float x = bg;
; #pragma unroll
;             for (int q = 0; q < 4; ++q) { const f32x4 f = fp[q]; x += f[0] * wg[4 * q] + f[1] * wg[4 * q + 1] + f[2] * wg[4 * q + 2] + f[3] * wg[4 * q + 3]; }
;             const float ls = fminf(x, 0.f) - __logf(1.0f + __expf(-fabsf(x))); run += ls * 0.0625f; Bimg[t * GBP + gd] = run;
;             if ((tt & 3) == 3) asm volatile("" ::: "memory"); }
	v_mul_f32_e32 v37, v22, v39
	v_fmac_f32_e32 v37, v20, v38
	s_waitcnt lgkmcnt(2)
	v_mul_f32_e32 v38, v24, v43
	v_fmac_f32_e32 v37, v25, v40
	v_fmac_f32_e32 v38, v21, v42
	v_fmac_f32_e32 v37, v23, v41
	v_fmac_f32_e32 v38, v29, v44
	v_add_f32_e32 v37, v2, v37
	v_fmac_f32_e32 v38, v27, v45
	v_add_f32_e32 v37, v37, v38
	s_waitcnt lgkmcnt(1)
	v_mul_f32_e32 v38, v28, v47
	v_fmac_f32_e32 v38, v26, v46
	v_fmac_f32_e32 v38, v33, v48
	v_fmac_f32_e32 v38, v31, v49
	v_add_f32_e32 v37, v37, v38
	s_waitcnt lgkmcnt(0)
	v_mul_f32_e32 v38, v32, v51
	v_fmac_f32_e32 v38, v30, v50
	v_fmac_f32_e32 v38, v34, v52
	v_fmac_f32_e32 v38, v35, v53
	v_add_f32_e32 v37, v37, v38
	v_min_f32_e32 v38, 0, v37
	v_mul_f32_e64 v37, |v37|, s93
	v_exp_f32_e32 v37, v37
	s_nop 0
	v_add_f32_e32 v37, 1.0, v37
	v_cmp_gt_f32_e64 s[62:63], s92, v37
	s_nop 1
	v_cndmask_b32_e64 v39, 0, 32, s[62:63]
	v_ldexp_f32 v37, v37, v39
	v_log_f32_e32 v37, v37
	s_nop 0
	v_mul_f32_e32 v39, 0x3f317217, v37
	v_fma_f32 v39, v37, s1, -v39
	v_fmac_f32_e32 v39, 0x3377d1cf, v37
	v_fmac_f32_e32 v39, 0x3f317217, v37
	v_cmp_lt_f32_e64 s[64:65], |v37|, s72
	s_nop 1
	v_cndmask_b32_e64 v37, v37, v39, s[64:65]
	v_cndmask_b32_e64 v39, 0, v208, s[62:63]
	v_sub_f32_e32 v37, v37, v39
	v_sub_f32_e32 v37, v38, v37
	v_fmac_f32_e32 v36, 0x3d800000, v37
	ds_write_b32 v138, v36 offset:528
	ds_read_b128 v[38:41], v155
	ds_read_b128 v[42:45], v155 offset:16
	ds_read_b128 v[46:49], v155 offset:32
	ds_read_b128 v[50:53], v155 offset:48
	s_waitcnt lgkmcnt(3)
	v_mul_f32_e32 v37, v22, v39
	v_fmac_f32_e32 v37, v20, v38
	s_waitcnt lgkmcnt(2)
	v_mul_f32_e32 v38, v24, v43
	v_fmac_f32_e32 v37, v25, v40
	v_fmac_f32_e32 v38, v21, v42
	v_fmac_f32_e32 v37, v23, v41
	v_fmac_f32_e32 v38, v29, v44
	v_add_f32_e32 v37, v2, v37
	v_fmac_f32_e32 v38, v27, v45
	v_add_f32_e32 v37, v37, v38
	s_waitcnt lgkmcnt(1)
	v_mul_f32_e32 v38, v28, v47
	v_fmac_f32_e32 v38, v26, v46
	v_fmac_f32_e32 v38, v33, v48
	v_fmac_f32_e32 v38, v31, v49
	v_add_f32_e32 v37, v37, v38
	s_waitcnt lgkmcnt(0)
	v_mul_f32_e32 v38, v32, v51
	v_fmac_f32_e32 v38, v30, v50
	v_fmac_f32_e32 v38, v34, v52
	v_fmac_f32_e32 v38, v35, v53
	v_add_f32_e32 v37, v37, v38
	v_min_f32_e32 v38, 0, v37
	v_mul_f32_e64 v37, |v37|, s93
	v_exp_f32_e32 v37, v37
	s_nop 0
	v_add_f32_e32 v37, 1.0, v37
	v_cmp_gt_f32_e64 s[62:63], s92, v37
	s_nop 1
	v_cndmask_b32_e64 v39, 0, 32, s[62:63]
	v_ldexp_f32 v37, v37, v39
	v_log_f32_e32 v37, v37
	s_nop 0
	v_mul_f32_e32 v39, 0x3f317217, v37
	v_fma_f32 v39, v37, s1, -v39
	v_fmac_f32_e32 v39, 0x3377d1cf, v37
	v_fmac_f32_e32 v39, 0x3f317217, v37
	v_cmp_lt_f32_e64 s[64:65], |v37|, s72
	s_nop 1
	v_cndmask_b32_e64 v37, v37, v39, s[64:65]
	v_cndmask_b32_e64 v39, 0, v208, s[62:63]
	v_sub_f32_e32 v37, v37, v39
	v_sub_f32_e32 v37, v38, v37
	v_fmac_f32_e32 v36, 0x3d800000, v37
	ds_write_b32 v138, v36 offset:1056
	ds_read_b128 v[38:41], v156
	ds_read_b128 v[42:45], v156 offset:16
	ds_read_b128 v[46:49], v156 offset:32
	ds_read_b128 v[50:53], v156 offset:48
	s_waitcnt lgkmcnt(3)
	v_mul_f32_e32 v37, v22, v39
	v_fmac_f32_e32 v37, v20, v38
	s_waitcnt lgkmcnt(2)
	v_mul_f32_e32 v38, v24, v43
	v_fmac_f32_e32 v37, v25, v40
	v_fmac_f32_e32 v38, v21, v42
	v_fmac_f32_e32 v37, v23, v41
	v_fmac_f32_e32 v38, v29, v44
	v_add_f32_e32 v37, v2, v37
	v_fmac_f32_e32 v38, v27, v45
	v_add_f32_e32 v37, v37, v38
	s_waitcnt lgkmcnt(1)
	v_mul_f32_e32 v38, v28, v47
	v_fmac_f32_e32 v38, v26, v46
	v_fmac_f32_e32 v38, v33, v48
	v_fmac_f32_e32 v38, v31, v49
	v_add_f32_e32 v37, v37, v38
	s_waitcnt lgkmcnt(0)
	v_mul_f32_e32 v38, v32, v51
	v_fmac_f32_e32 v38, v30, v50
	v_fmac_f32_e32 v38, v34, v52
	v_fmac_f32_e32 v38, v35, v53
	v_add_f32_e32 v37, v37, v38
	v_min_f32_e32 v38, 0, v37
	v_mul_f32_e64 v37, |v37|, s93
	v_exp_f32_e32 v37, v37
	s_nop 0
	v_add_f32_e32 v37, 1.0, v37
	v_cmp_gt_f32_e64 s[62:63], s92, v37
	s_nop 1
	v_cndmask_b32_e64 v39, 0, 32, s[62:63]
	v_ldexp_f32 v37, v37, v39
	v_log_f32_e32 v37, v37
	s_nop 0
	v_mul_f32_e32 v39, 0x3f317217, v37
	v_fma_f32 v39, v37, s1, -v39
	v_fmac_f32_e32 v39, 0x3377d1cf, v37
	v_fmac_f32_e32 v39, 0x3f317217, v37
	v_cmp_lt_f32_e64 s[64:65], |v37|, s72
	s_nop 1
	v_cndmask_b32_e64 v37, v37, v39, s[64:65]
	v_cndmask_b32_e64 v39, 0, v208, s[62:63]
	v_sub_f32_e32 v37, v37, v39
	v_sub_f32_e32 v37, v38, v37
	v_fmac_f32_e32 v36, 0x3d800000, v37
	ds_write_b32 v138, v36 offset:1584
	ds_read_b128 v[38:41], v157
	ds_read_b128 v[42:45], v157 offset:16
	ds_read_b128 v[46:49], v157 offset:32
	ds_read_b128 v[50:53], v157 offset:48
	s_waitcnt lgkmcnt(3)
	v_mul_f32_e32 v37, v22, v39
	v_fmac_f32_e32 v37, v20, v38
	s_waitcnt lgkmcnt(2)
	v_mul_f32_e32 v38, v24, v43
	v_fmac_f32_e32 v37, v25, v40
	v_fmac_f32_e32 v38, v21, v42
	v_fmac_f32_e32 v37, v23, v41
	v_fmac_f32_e32 v38, v29, v44
	v_add_f32_e32 v37, v2, v37
	v_fmac_f32_e32 v38, v27, v45
	v_add_f32_e32 v37, v37, v38
	s_waitcnt lgkmcnt(1)
	v_mul_f32_e32 v38, v28, v47
	v_fmac_f32_e32 v38, v26, v46
	v_fmac_f32_e32 v38, v33, v48
	v_fmac_f32_e32 v38, v31, v49
	v_add_f32_e32 v37, v37, v38
	s_waitcnt lgkmcnt(0)
	v_mul_f32_e32 v38, v32, v51
	v_fmac_f32_e32 v38, v30, v50
	v_fmac_f32_e32 v38, v34, v52
	v_fmac_f32_e32 v38, v35, v53
	v_add_f32_e32 v37, v37, v38
	v_min_f32_e32 v38, 0, v37
	v_mul_f32_e64 v37, |v37|, s93
	v_exp_f32_e32 v37, v37
	s_nop 0
	v_add_f32_e32 v37, 1.0, v37
	v_cmp_gt_f32_e64 s[62:63], s92, v37
	s_nop 1
	v_cndmask_b32_e64 v39, 0, 32, s[62:63]
	v_ldexp_f32 v37, v37, v39
	v_log_f32_e32 v37, v37
	s_nop 0
	v_mul_f32_e32 v39, 0x3f317217, v37
	v_fma_f32 v39, v37, s1, -v39
	v_fmac_f32_e32 v39, 0x3377d1cf, v37
	v_fmac_f32_e32 v39, 0x3f317217, v37
	v_cmp_lt_f32_e64 s[64:65], |v37|, s72
	s_nop 1
	v_cndmask_b32_e64 v37, v37, v39, s[64:65]
	v_cndmask_b32_e64 v39, 0, v208, s[62:63]
	v_sub_f32_e32 v37, v37, v39
	v_sub_f32_e32 v37, v38, v37
	v_fmac_f32_e32 v36, 0x3d800000, v37
	ds_write_b32 v138, v36 offset:2112
	ds_read_b128 v[38:41], v158
	ds_read_b128 v[42:45], v158 offset:16
	ds_read_b128 v[46:49], v158 offset:32
	ds_read_b128 v[50:53], v158 offset:48
	s_waitcnt lgkmcnt(3)
; #define LAS __attribute__((address_space(3)))
; __device__ __forceinline__ void gla_a_unit(LAS unsigned char* lds, bf16* QKA, bf16* VA, const float* FA, unsigned char* ws, int xnrow0, float* DECB, int lchunk, int h,
;                                            const float* wgate, const float* bgate, int tid) {
;     ...
;         float run = 0.f;
; #pragma unroll
;         for (int tt = 0; tt < 16; ++tt) { const int t = tq * 16 + tt; const LAS f32x4* fp = (const LAS f32x4*)(FAi + t * 16); float x = bg;
; #pragma unroll
;             for (int q = 0; q < 4; ++q) { const f32x4 f = fp[q]; x += f[0] * wg[4 * q] + f[1] * wg[4 * q + 1] + f[2] * wg[4 * q + 2] + f[3] * wg[4 * q + 3]; }
;             const float ls = fminf(x, 0.f) - __logf(1.0f + __expf(-fabsf(x))); run += ls * 0.0625f; Bimg[t * GBP + gd] = run;
;             if ((tt & 3) == 3) asm volatile("" ::: "memory"); }
	v_mul_f32_e32 v37, v22, v39
	v_fmac_f32_e32 v37, v20, v38
	s_waitcnt lgkmcnt(2)
	v_mul_f32_e32 v38, v24, v43
	v_fmac_f32_e32 v37, v25, v40
	v_fmac_f32_e32 v38, v21, v42
	v_fmac_f32_e32 v37, v23, v41
	v_fmac_f32_e32 v38, v29, v44
	v_add_f32_e32 v37, v2, v37
	v_fmac_f32_e32 v38, v27, v45
	v_add_f32_e32 v37, v37, v38
	s_waitcnt lgkmcnt(1)
	v_mul_f32_e32 v38, v28, v47
	v_fmac_f32_e32 v38, v26, v46
	v_fmac_f32_e32 v38, v33, v48
	v_fmac_f32_e32 v38, v31, v49
	v_add_f32_e32 v37, v37, v38
	s_waitcnt lgkmcnt(0)
	v_mul_f32_e32 v38, v32, v51
	v_fmac_f32_e32 v38, v30, v50
	v_fmac_f32_e32 v38, v34, v52
	v_fmac_f32_e32 v38, v35, v53
	v_add_f32_e32 v37, v37, v38
	v_min_f32_e32 v38, 0, v37
	v_mul_f32_e64 v37, |v37|, s93
	v_exp_f32_e32 v37, v37
	s_nop 0
	v_add_f32_e32 v37, 1.0, v37
	v_cmp_gt_f32_e64 s[62:63], s92, v37
	s_nop 1
	v_cndmask_b32_e64 v39, 0, 32, s[62:63]
	v_ldexp_f32 v37, v37, v39
	v_log_f32_e32 v37, v37
	s_nop 0
	v_mul_f32_e32 v39, 0x3f317217, v37
	v_fma_f32 v39, v37, s1, -v39
	v_fmac_f32_e32 v39, 0x3377d1cf, v37
	v_fmac_f32_e32 v39, 0x3f317217, v37
	v_cmp_lt_f32_e64 s[64:65], |v37|, s72
	s_nop 1
	v_cndmask_b32_e64 v37, v37, v39, s[64:65]
	v_cndmask_b32_e64 v39, 0, v208, s[62:63]
	v_sub_f32_e32 v37, v37, v39
	v_sub_f32_e32 v37, v38, v37
	v_fmac_f32_e32 v36, 0x3d800000, v37
	ds_write_b32 v138, v36 offset:2640
	ds_read_b128 v[38:41], v159
	ds_read_b128 v[42:45], v159 offset:16
	ds_read_b128 v[46:49], v159 offset:32
	ds_read_b128 v[50:53], v159 offset:48
	s_waitcnt lgkmcnt(3)
	v_mul_f32_e32 v37, v22, v39
	v_fmac_f32_e32 v37, v20, v38
	s_waitcnt lgkmcnt(2)
	v_mul_f32_e32 v38, v24, v43
	v_fmac_f32_e32 v37, v25, v40
	v_fmac_f32_e32 v38, v21, v42
	v_fmac_f32_e32 v37, v23, v41
	v_fmac_f32_e32 v38, v29, v44
	v_add_f32_e32 v37, v2, v37
	v_fmac_f32_e32 v38, v27, v45
	v_add_f32_e32 v37, v37, v38
	s_waitcnt lgkmcnt(1)
	v_mul_f32_e32 v38, v28, v47
	v_fmac_f32_e32 v38, v26, v46
	v_fmac_f32_e32 v38, v33, v48
	v_fmac_f32_e32 v38, v31, v49
	v_add_f32_e32 v37, v37, v38
	s_waitcnt lgkmcnt(0)
	v_mul_f32_e32 v38, v32, v51
	v_fmac_f32_e32 v38, v30, v50
	v_fmac_f32_e32 v38, v34, v52
	v_fmac_f32_e32 v38, v35, v53
	v_add_f32_e32 v37, v37, v38
	v_min_f32_e32 v38, 0, v37
	v_mul_f32_e64 v37, |v37|, s93
	v_exp_f32_e32 v37, v37
	s_nop 0
	v_add_f32_e32 v37, 1.0, v37
	v_cmp_gt_f32_e64 s[62:63], s92, v37
	s_nop 1
	v_cndmask_b32_e64 v39, 0, 32, s[62:63]
	v_ldexp_f32 v37, v37, v39
	v_log_f32_e32 v37, v37
	s_nop 0
	v_mul_f32_e32 v39, 0x3f317217, v37
	v_fma_f32 v39, v37, s1, -v39
	v_fmac_f32_e32 v39, 0x3377d1cf, v37
	v_fmac_f32_e32 v39, 0x3f317217, v37
	v_cmp_lt_f32_e64 s[64:65], |v37|, s72
	s_nop 1
	v_cndmask_b32_e64 v37, v37, v39, s[64:65]
	v_cndmask_b32_e64 v39, 0, v208, s[62:63]
	v_sub_f32_e32 v37, v37, v39
	v_sub_f32_e32 v37, v38, v37
	v_fmac_f32_e32 v36, 0x3d800000, v37
	ds_write_b32 v138, v36 offset:3168
	ds_read_b128 v[38:41], v160
	ds_read_b128 v[42:45], v160 offset:16
	ds_read_b128 v[46:49], v160 offset:32
	ds_read_b128 v[50:53], v160 offset:48
	s_waitcnt lgkmcnt(3)
	v_mul_f32_e32 v37, v22, v39
	v_fmac_f32_e32 v37, v20, v38
	s_waitcnt lgkmcnt(2)
	v_mul_f32_e32 v38, v24, v43
	v_fmac_f32_e32 v37, v25, v40
	v_fmac_f32_e32 v38, v21, v42
	v_fmac_f32_e32 v37, v23, v41
	v_fmac_f32_e32 v38, v29, v44
	v_add_f32_e32 v37, v2, v37
	v_fmac_f32_e32 v38, v27, v45
	v_add_f32_e32 v37, v37, v38
	s_waitcnt lgkmcnt(1)
	v_mul_f32_e32 v38, v28, v47
	v_fmac_f32_e32 v38, v26, v46
	v_fmac_f32_e32 v38, v33, v48
	v_fmac_f32_e32 v38, v31, v49
	v_add_f32_e32 v37, v37, v38
	s_waitcnt lgkmcnt(0)
	v_mul_f32_e32 v38, v32, v51
	v_fmac_f32_e32 v38, v30, v50
	v_fmac_f32_e32 v38, v34, v52
	v_fmac_f32_e32 v38, v35, v53
	v_add_f32_e32 v37, v37, v38
	v_min_f32_e32 v38, 0, v37
	v_mul_f32_e64 v37, |v37|, s93
	v_exp_f32_e32 v37, v37
	s_nop 0
	v_add_f32_e32 v37, 1.0, v37
	v_cmp_gt_f32_e64 s[62:63], s92, v37
	s_nop 1
	v_cndmask_b32_e64 v39, 0, 32, s[62:63]
	v_ldexp_f32 v37, v37, v39
	v_log_f32_e32 v37, v37
	s_nop 0
	v_mul_f32_e32 v39, 0x3f317217, v37
	v_fma_f32 v39, v37, s1, -v39
	v_fmac_f32_e32 v39, 0x3377d1cf, v37
	v_fmac_f32_e32 v39, 0x3f317217, v37
	v_cmp_lt_f32_e64 s[64:65], |v37|, s72
	s_nop 1
	v_cndmask_b32_e64 v37, v37, v39, s[64:65]
	v_cndmask_b32_e64 v39, 0, v208, s[62:63]
	v_sub_f32_e32 v37, v37, v39
	v_sub_f32_e32 v37, v38, v37
	v_fmac_f32_e32 v36, 0x3d800000, v37
	ds_write_b32 v138, v36 offset:3696
	ds_read_b128 v[38:41], v161
	ds_read_b128 v[42:45], v161 offset:16
	ds_read_b128 v[46:49], v161 offset:32
	ds_read_b128 v[50:53], v161 offset:48
	s_waitcnt lgkmcnt(3)
	v_mul_f32_e32 v37, v22, v39
	v_fmac_f32_e32 v37, v20, v38
	s_waitcnt lgkmcnt(2)
	v_mul_f32_e32 v38, v24, v43
	v_fmac_f32_e32 v37, v25, v40
	v_fmac_f32_e32 v38, v21, v42
	v_fmac_f32_e32 v37, v23, v41
	v_fmac_f32_e32 v38, v29, v44
	v_add_f32_e32 v37, v2, v37
	v_fmac_f32_e32 v38, v27, v45
	v_add_f32_e32 v37, v37, v38
	s_waitcnt lgkmcnt(1)
	v_mul_f32_e32 v38, v28, v47
	v_fmac_f32_e32 v38, v26, v46
	v_fmac_f32_e32 v38, v33, v48
	v_fmac_f32_e32 v38, v31, v49
	v_add_f32_e32 v37, v37, v38
	s_waitcnt lgkmcnt(0)
	v_mul_f32_e32 v38, v32, v51
	v_fmac_f32_e32 v38, v30, v50
	v_fmac_f32_e32 v38, v34, v52
	v_fmac_f32_e32 v38, v35, v53
	v_add_f32_e32 v37, v37, v38
	v_min_f32_e32 v38, 0, v37
	v_mul_f32_e64 v37, |v37|, s93
	v_exp_f32_e32 v37, v37
	s_nop 0
	v_add_f32_e32 v37, 1.0, v37
	v_cmp_gt_f32_e64 s[62:63], s92, v37
	s_nop 1
	v_cndmask_b32_e64 v39, 0, 32, s[62:63]
	v_ldexp_f32 v37, v37, v39
	v_log_f32_e32 v37, v37
	s_nop 0
	v_mul_f32_e32 v39, 0x3f317217, v37
	v_fma_f32 v39, v37, s1, -v39
	v_fmac_f32_e32 v39, 0x3377d1cf, v37
	v_fmac_f32_e32 v39, 0x3f317217, v37
	v_cmp_lt_f32_e64 s[64:65], |v37|, s72
	s_nop 1
	v_cndmask_b32_e64 v37, v37, v39, s[64:65]
	v_cndmask_b32_e64 v39, 0, v208, s[62:63]
	v_sub_f32_e32 v37, v37, v39
	v_sub_f32_e32 v37, v38, v37
	v_fmac_f32_e32 v36, 0x3d800000, v37
	ds_write_b32 v138, v36 offset:4224
	ds_read_b128 v[38:41], v162
	ds_read_b128 v[42:45], v162 offset:16
	ds_read_b128 v[46:49], v162 offset:32
	ds_read_b128 v[50:53], v162 offset:48
	s_waitcnt lgkmcnt(3)
; #define LAS __attribute__((address_space(3)))
; __device__ __forceinline__ void gla_a_unit(LAS unsigned char* lds, bf16* QKA, bf16* VA, const float* FA, unsigned char* ws, int xnrow0, float* DECB, int lchunk, int h,
;                                            const float* wgate, const float* bgate, int tid) {
;     ...
;         float run = 0.f;
; #pragma unroll
;         for (int tt = 0; tt < 16; ++tt) { const int t = tq * 16 + tt; const LAS f32x4* fp = (const LAS f32x4*)(FAi + t * 16); float x = bg;
; #pragma unroll
;             for (int q = 0; q < 4; ++q) { const f32x4 f = fp[q]; x += f[0] * wg[4 * q] + f[1] * wg[4 * q + 1] + f[2] * wg[4 * q + 2] + f[3] * wg[4 * q + 3]; }
;             const float ls = fminf(x, 0.f) - __logf(1.0f + __expf(-fabsf(x))); run += ls * 0.0625f; Bimg[t * GBP + gd] = run;
;             if ((tt & 3) == 3) asm volatile("" ::: "memory"); }
	v_mul_f32_e32 v37, v22, v39
	v_fmac_f32_e32 v37, v20, v38
	s_waitcnt lgkmcnt(2)
	v_mul_f32_e32 v38, v24, v43
	v_fmac_f32_e32 v37, v25, v40
	v_fmac_f32_e32 v38, v21, v42
	v_fmac_f32_e32 v37, v23, v41
	v_fmac_f32_e32 v38, v29, v44
	v_add_f32_e32 v37, v2, v37
	v_fmac_f32_e32 v38, v27, v45
	v_add_f32_e32 v37, v37, v38
	s_waitcnt lgkmcnt(1)
	v_mul_f32_e32 v38, v28, v47
	v_fmac_f32_e32 v38, v26, v46
	v_fmac_f32_e32 v38, v33, v48
	v_fmac_f32_e32 v38, v31, v49
	v_add_f32_e32 v37, v37, v38
	s_waitcnt lgkmcnt(0)
	v_mul_f32_e32 v38, v32, v51
	v_fmac_f32_e32 v38, v30, v50
	v_fmac_f32_e32 v38, v34, v52
	v_fmac_f32_e32 v38, v35, v53
	v_add_f32_e32 v37, v37, v38
	v_min_f32_e32 v38, 0, v37
	v_mul_f32_e64 v37, |v37|, s93
	v_exp_f32_e32 v37, v37
	s_nop 0
	v_add_f32_e32 v37, 1.0, v37
	v_cmp_gt_f32_e64 s[62:63], s92, v37
	s_nop 1
	v_cndmask_b32_e64 v39, 0, 32, s[62:63]
	v_ldexp_f32 v37, v37, v39
	v_log_f32_e32 v37, v37
	s_nop 0
	v_mul_f32_e32 v39, 0x3f317217, v37
	v_fma_f32 v39, v37, s1, -v39
	v_fmac_f32_e32 v39, 0x3377d1cf, v37
	v_fmac_f32_e32 v39, 0x3f317217, v37
	v_cmp_lt_f32_e64 s[64:65], |v37|, s72
	s_nop 1
	v_cndmask_b32_e64 v37, v37, v39, s[64:65]
	v_cndmask_b32_e64 v39, 0, v208, s[62:63]
	v_sub_f32_e32 v37, v37, v39
	v_sub_f32_e32 v37, v38, v37
	v_fmac_f32_e32 v36, 0x3d800000, v37
	ds_write_b32 v138, v36 offset:4752
	ds_read_b128 v[38:41], v163
	ds_read_b128 v[42:45], v163 offset:16
	ds_read_b128 v[46:49], v163 offset:32
	ds_read_b128 v[50:53], v163 offset:48
	s_waitcnt lgkmcnt(3)
	v_mul_f32_e32 v37, v22, v39
	v_fmac_f32_e32 v37, v20, v38
	s_waitcnt lgkmcnt(2)
	v_mul_f32_e32 v38, v24, v43
	v_fmac_f32_e32 v37, v25, v40
	v_fmac_f32_e32 v38, v21, v42
	v_fmac_f32_e32 v37, v23, v41
	v_fmac_f32_e32 v38, v29, v44
	v_add_f32_e32 v37, v2, v37
	v_fmac_f32_e32 v38, v27, v45
	v_add_f32_e32 v37, v37, v38
	s_waitcnt lgkmcnt(1)
	v_mul_f32_e32 v38, v28, v47
	v_fmac_f32_e32 v38, v26, v46
	v_fmac_f32_e32 v38, v33, v48
	v_fmac_f32_e32 v38, v31, v49
	v_add_f32_e32 v37, v37, v38
	s_waitcnt lgkmcnt(0)
	v_mul_f32_e32 v38, v32, v51
	v_fmac_f32_e32 v38, v30, v50
	v_fmac_f32_e32 v38, v34, v52
	v_fmac_f32_e32 v38, v35, v53
	v_add_f32_e32 v37, v37, v38
	v_min_f32_e32 v38, 0, v37
	v_mul_f32_e64 v37, |v37|, s93
	v_exp_f32_e32 v37, v37
	s_nop 0
	v_add_f32_e32 v37, 1.0, v37
	v_cmp_gt_f32_e64 s[62:63], s92, v37
	s_nop 1
	v_cndmask_b32_e64 v39, 0, 32, s[62:63]
	v_ldexp_f32 v37, v37, v39
	v_log_f32_e32 v37, v37
	s_nop 0
	v_mul_f32_e32 v39, 0x3f317217, v37
	v_fma_f32 v39, v37, s1, -v39
	v_fmac_f32_e32 v39, 0x3377d1cf, v37
	v_fmac_f32_e32 v39, 0x3f317217, v37
	v_cmp_lt_f32_e64 s[64:65], |v37|, s72
	s_nop 1
	v_cndmask_b32_e64 v37, v37, v39, s[64:65]
	v_cndmask_b32_e64 v39, 0, v208, s[62:63]
	v_sub_f32_e32 v37, v37, v39
	v_sub_f32_e32 v37, v38, v37
	v_fmac_f32_e32 v36, 0x3d800000, v37
	ds_write_b32 v138, v36 offset:5280
	ds_read_b128 v[38:41], v164
	ds_read_b128 v[42:45], v164 offset:16
	ds_read_b128 v[46:49], v164 offset:32
	ds_read_b128 v[50:53], v164 offset:48
	s_waitcnt lgkmcnt(3)
	v_mul_f32_e32 v37, v22, v39
	v_fmac_f32_e32 v37, v20, v38
	s_waitcnt lgkmcnt(2)
	v_mul_f32_e32 v38, v24, v43
	v_fmac_f32_e32 v37, v25, v40
	v_fmac_f32_e32 v38, v21, v42
	v_fmac_f32_e32 v37, v23, v41
	v_fmac_f32_e32 v38, v29, v44
	v_add_f32_e32 v37, v2, v37
	v_fmac_f32_e32 v38, v27, v45
	v_add_f32_e32 v37, v37, v38
	s_waitcnt lgkmcnt(1)
	v_mul_f32_e32 v38, v28, v47
	v_fmac_f32_e32 v38, v26, v46
	v_fmac_f32_e32 v38, v33, v48
	v_fmac_f32_e32 v38, v31, v49
	v_add_f32_e32 v37, v37, v38
	s_waitcnt lgkmcnt(0)
	v_mul_f32_e32 v38, v32, v51
	v_fmac_f32_e32 v38, v30, v50
	v_fmac_f32_e32 v38, v34, v52
	v_fmac_f32_e32 v38, v35, v53
	v_add_f32_e32 v37, v37, v38
	v_min_f32_e32 v38, 0, v37
	v_mul_f32_e64 v37, |v37|, s93
	v_exp_f32_e32 v37, v37
	s_nop 0
	v_add_f32_e32 v37, 1.0, v37
	v_cmp_gt_f32_e64 s[62:63], s92, v37
	s_nop 1
	v_cndmask_b32_e64 v39, 0, 32, s[62:63]
	v_ldexp_f32 v37, v37, v39
	v_log_f32_e32 v37, v37
	s_nop 0
	v_mul_f32_e32 v39, 0x3f317217, v37
	v_fma_f32 v39, v37, s1, -v39
	v_fmac_f32_e32 v39, 0x3377d1cf, v37
	v_fmac_f32_e32 v39, 0x3f317217, v37
	v_cmp_lt_f32_e64 s[64:65], |v37|, s72
	s_nop 1
	v_cndmask_b32_e64 v37, v37, v39, s[64:65]
	v_cndmask_b32_e64 v39, 0, v208, s[62:63]
	v_sub_f32_e32 v37, v37, v39
	v_sub_f32_e32 v37, v38, v37
	v_fmac_f32_e32 v36, 0x3d800000, v37
	ds_write_b32 v138, v36 offset:5808
	ds_read_b128 v[38:41], v165
	ds_read_b128 v[42:45], v165 offset:16
	ds_read_b128 v[46:49], v165 offset:32
	ds_read_b128 v[50:53], v165 offset:48
	s_waitcnt lgkmcnt(3)
	v_mul_f32_e32 v37, v22, v39
	v_fmac_f32_e32 v37, v20, v38
	s_waitcnt lgkmcnt(2)
	v_mul_f32_e32 v38, v24, v43
	v_fmac_f32_e32 v37, v25, v40
	v_fmac_f32_e32 v38, v21, v42
	v_fmac_f32_e32 v37, v23, v41
	v_fmac_f32_e32 v38, v29, v44
	v_add_f32_e32 v37, v2, v37
	v_fmac_f32_e32 v38, v27, v45
	v_add_f32_e32 v37, v37, v38
	s_waitcnt lgkmcnt(1)
	v_mul_f32_e32 v38, v28, v47
	v_fmac_f32_e32 v38, v26, v46
	v_fmac_f32_e32 v38, v33, v48
	v_fmac_f32_e32 v38, v31, v49
	v_add_f32_e32 v37, v37, v38
	s_waitcnt lgkmcnt(0)
	v_mul_f32_e32 v38, v32, v51
	v_fmac_f32_e32 v38, v30, v50
	v_fmac_f32_e32 v38, v34, v52
	v_fmac_f32_e32 v38, v35, v53
	v_add_f32_e32 v37, v37, v38
	v_min_f32_e32 v38, 0, v37
	v_mul_f32_e64 v37, |v37|, s93
	v_exp_f32_e32 v37, v37
	s_nop 0
	v_add_f32_e32 v37, 1.0, v37
	v_cmp_gt_f32_e64 s[62:63], s92, v37
	s_nop 1
	v_cndmask_b32_e64 v39, 0, 32, s[62:63]
	v_ldexp_f32 v37, v37, v39
	v_log_f32_e32 v37, v37
	s_nop 0
	v_mul_f32_e32 v39, 0x3f317217, v37
	v_fma_f32 v39, v37, s1, -v39
	v_fmac_f32_e32 v39, 0x3377d1cf, v37
	v_fmac_f32_e32 v39, 0x3f317217, v37
	v_cmp_lt_f32_e64 s[64:65], |v37|, s72
	s_nop 1
	v_cndmask_b32_e64 v37, v37, v39, s[64:65]
	v_cndmask_b32_e64 v39, 0, v208, s[62:63]
	v_sub_f32_e32 v37, v37, v39
	v_sub_f32_e32 v37, v38, v37
	v_fmac_f32_e32 v36, 0x3d800000, v37
	ds_write_b32 v138, v36 offset:6336
	ds_read_b128 v[38:41], v166
	ds_read_b128 v[42:45], v166 offset:16
	ds_read_b128 v[46:49], v166 offset:32
	ds_read_b128 v[50:53], v166 offset:48
	s_waitcnt lgkmcnt(3)
; #define LAS __attribute__((address_space(3)))
; __device__ __forceinline__ void gla_a_unit(LAS unsigned char* lds, bf16* QKA, bf16* VA, const float* FA, unsigned char* ws, int xnrow0, float* DECB, int lchunk, int h,
;                                            const float* wgate, const float* bgate, int tid) {
;     ...
;         for (int tt = 0; tt < 16; ++tt) { const int t = tq * 16 + tt; const LAS f32x4* fp = (const LAS f32x4*)(FAi + t * 16); float x = bg;
; #pragma unroll
;             for (int q = 0; q < 4; ++q) { const f32x4 f = fp[q]; x += f[0] * wg[4 * q] + f[1] * wg[4 * q + 1] + f[2] * wg[4 * q + 2] + f[3] * wg[4 * q + 3]; }
;             const float ls = fminf(x, 0.f) - __logf(1.0f + __expf(-fabsf(x))); run += ls * 0.0625f; Bimg[t * GBP + gd] = run;
;             if ((tt & 3) == 3) asm volatile("" ::: "memory"); }
;         SEG[tq * 128 + gd] = run;
;     }
;     __syncthreads();
; #pragma unroll
;     for (int i = 0; i < 2; ++i) { const int id = tid + 512 * i, row = id >> 4, ch = id & 15;
;         f32x4 b0 = *(const LAS f32x4*)(Bimg + row * GBP + ch * 8), b1 = *(const LAS f32x4*)(Bimg + row * GBP + ch * 8 + 4);
;         f32x4 l0 = (f32x4){0.f, 0.f, 0.f, 0.f}, l1 = l0;
; #pragma unroll
;         for (int q = 0; q < 4; ++q) { const f32x4 s0v = *(const LAS f32x4*)(SEG + q * 128 + ch * 8), s1v = *(const LAS f32x4*)(SEG + q * 128 + ch * 8 + 4);
;             l0 += s0v; l1 += s1v; if (q < (row >> 4)) { b0 += s0v; b1 += s1v; } }
;         if (row == 0) { float* dp = DECB + (size_t)unit * 128 + ch * 8;
;             *(f32x4*)dp = (f32x4){__expf(l0[0]), __expf(l0[1]), __expf(l0[2]), __expf(l0[3])}; *(f32x4*)(dp + 4) = (f32x4){__expf(l1[0]), __expf(l1[1]), __expf(l1[2]), __expf(l1[3])}; }
	v_mul_f32_e32 v37, v22, v39
	v_fmac_f32_e32 v37, v20, v38
	s_waitcnt lgkmcnt(2)
	v_mul_f32_e32 v38, v24, v43
	v_fmac_f32_e32 v37, v25, v40
	v_fmac_f32_e32 v38, v21, v42
	v_fmac_f32_e32 v37, v23, v41
	v_fmac_f32_e32 v38, v29, v44
	v_add_f32_e32 v37, v2, v37
	v_fmac_f32_e32 v38, v27, v45
	v_add_f32_e32 v37, v37, v38
	s_waitcnt lgkmcnt(1)
	v_mul_f32_e32 v38, v28, v47
	v_fmac_f32_e32 v38, v26, v46
	v_fmac_f32_e32 v38, v33, v48
	v_fmac_f32_e32 v38, v31, v49
	v_add_f32_e32 v37, v37, v38
	s_waitcnt lgkmcnt(0)
	v_mul_f32_e32 v38, v32, v51
	v_fmac_f32_e32 v38, v30, v50
	v_fmac_f32_e32 v38, v34, v52
	v_fmac_f32_e32 v38, v35, v53
	v_add_f32_e32 v37, v37, v38
	v_min_f32_e32 v38, 0, v37
	v_mul_f32_e64 v37, |v37|, s93
	v_exp_f32_e32 v37, v37
	s_nop 0
	v_add_f32_e32 v37, 1.0, v37
	v_cmp_gt_f32_e64 s[62:63], s92, v37
	s_nop 1
	v_cndmask_b32_e64 v39, 0, 32, s[62:63]
	v_ldexp_f32 v37, v37, v39
	v_log_f32_e32 v37, v37
	s_nop 0
	v_mul_f32_e32 v39, 0x3f317217, v37
	v_fma_f32 v39, v37, s1, -v39
	v_fmac_f32_e32 v39, 0x3377d1cf, v37
	v_fmac_f32_e32 v39, 0x3f317217, v37
	v_cmp_lt_f32_e64 s[64:65], |v37|, s72
	s_nop 1
	v_cndmask_b32_e64 v37, v37, v39, s[64:65]
	v_cndmask_b32_e64 v39, 0, v208, s[62:63]
	v_sub_f32_e32 v37, v37, v39
	v_sub_f32_e32 v37, v38, v37
	v_fmac_f32_e32 v36, 0x3d800000, v37
	ds_write_b32 v138, v36 offset:6864
	ds_read_b128 v[38:41], v167
	ds_read_b128 v[42:45], v167 offset:16
	ds_read_b128 v[46:49], v167 offset:32
	ds_read_b128 v[50:53], v167 offset:48
	s_waitcnt lgkmcnt(3)
	v_mul_f32_e32 v37, v22, v39
	v_fmac_f32_e32 v37, v20, v38
	s_waitcnt lgkmcnt(2)
	v_mul_f32_e32 v38, v24, v43
	v_fmac_f32_e32 v37, v25, v40
	v_fmac_f32_e32 v38, v21, v42
	v_fmac_f32_e32 v37, v23, v41
	v_fmac_f32_e32 v38, v29, v44
	v_add_f32_e32 v37, v2, v37
	v_fmac_f32_e32 v38, v27, v45
	v_add_f32_e32 v37, v37, v38
	s_waitcnt lgkmcnt(1)
	v_mul_f32_e32 v38, v28, v47
	v_fmac_f32_e32 v38, v26, v46
	v_fmac_f32_e32 v38, v33, v48
	v_fmac_f32_e32 v38, v31, v49
	v_add_f32_e32 v37, v37, v38
	s_waitcnt lgkmcnt(0)
	v_mul_f32_e32 v38, v32, v51
	v_fmac_f32_e32 v38, v30, v50
	v_fmac_f32_e32 v38, v34, v52
	v_fmac_f32_e32 v38, v35, v53
	v_add_f32_e32 v37, v37, v38
	v_min_f32_e32 v38, 0, v37
	v_mul_f32_e64 v37, |v37|, s93
	v_exp_f32_e32 v37, v37
	s_nop 0
	v_add_f32_e32 v37, 1.0, v37
	v_cmp_gt_f32_e64 s[62:63], s92, v37
	s_nop 1
	v_cndmask_b32_e64 v39, 0, 32, s[62:63]
	v_ldexp_f32 v37, v37, v39
	v_log_f32_e32 v37, v37
	s_nop 0
	v_mul_f32_e32 v39, 0x3f317217, v37
	v_fma_f32 v39, v37, s1, -v39
	v_fmac_f32_e32 v39, 0x3377d1cf, v37
	v_fmac_f32_e32 v39, 0x3f317217, v37
	v_cmp_lt_f32_e64 s[64:65], |v37|, s72
	s_nop 1
	v_cndmask_b32_e64 v37, v37, v39, s[64:65]
	v_cndmask_b32_e64 v39, 0, v208, s[62:63]
	v_sub_f32_e32 v37, v37, v39
	v_sub_f32_e32 v37, v38, v37
	v_fmac_f32_e32 v36, 0x3d800000, v37
	ds_write_b32 v138, v36 offset:7392
	ds_read_b128 v[38:41], v168
	ds_read_b128 v[42:45], v168 offset:16
	ds_read_b128 v[46:49], v168 offset:32
	ds_read_b128 v[50:53], v168 offset:48
	s_waitcnt lgkmcnt(3)
	v_mul_f32_e32 v22, v22, v39
	v_fmac_f32_e32 v22, v20, v38
	s_waitcnt lgkmcnt(2)
	v_mul_f32_e32 v20, v24, v43
	v_fmac_f32_e32 v22, v25, v40
	v_fmac_f32_e32 v20, v21, v42
	v_fmac_f32_e32 v22, v23, v41
	v_fmac_f32_e32 v20, v29, v44
	v_add_f32_e32 v2, v2, v22
	v_fmac_f32_e32 v20, v27, v45
	v_add_f32_e32 v2, v2, v20
	s_waitcnt lgkmcnt(1)
	v_mul_f32_e32 v20, v28, v47
	v_fmac_f32_e32 v20, v26, v46
	v_fmac_f32_e32 v20, v33, v48
	v_fmac_f32_e32 v20, v31, v49
	v_add_f32_e32 v2, v2, v20
	s_waitcnt lgkmcnt(0)
	v_mul_f32_e32 v20, v32, v51
	v_fmac_f32_e32 v20, v30, v50
	v_fmac_f32_e32 v20, v34, v52
	v_fmac_f32_e32 v20, v35, v53
	v_add_f32_e32 v2, v2, v20
	v_min_f32_e32 v20, 0, v2
	v_mul_f32_e64 v2, |v2|, s93
	v_exp_f32_e32 v2, v2
	s_nop 0
	v_add_f32_e32 v2, 1.0, v2
	v_cmp_gt_f32_e64 s[62:63], s92, v2
	s_nop 1
	v_cndmask_b32_e64 v21, 0, 32, s[62:63]
	v_ldexp_f32 v2, v2, v21
	v_log_f32_e32 v2, v2
	s_nop 0
	v_mul_f32_e32 v21, 0x3f317217, v2
	v_fma_f32 v21, v2, s1, -v21
	v_fmac_f32_e32 v21, 0x3377d1cf, v2
	v_fmac_f32_e32 v21, 0x3f317217, v2
	v_cmp_lt_f32_e64 s[64:65], |v2|, s72
	s_nop 1
	v_cndmask_b32_e64 v2, v2, v21, s[64:65]
	v_cndmask_b32_e64 v21, 0, v208, s[62:63]
	v_sub_f32_e32 v2, v2, v21
	v_sub_f32_e32 v2, v20, v2
	v_fmac_f32_e32 v36, 0x3d800000, v2
	v_lshl_add_u64 v[20:21], v[122:123], 0, s[88:89]
	ds_write_b32 v139, v36
	v_lshl_add_u64 v[66:67], v[20:21], 0, s[6:7]
	s_mov_b64 s[6:7], 0x4200010
	ds_write_b32 v129, v36
	s_waitcnt lgkmcnt(0)
	s_barrier
	v_lshl_add_u64 v[64:65], v[20:21], 0, s[6:7]
	ds_read_b128 v[44:47], v146
	ds_read_b128 v[48:51], v146 offset:16
	ds_read_b128 v[56:59], v130
	ds_read_b128 v[52:55], v130 offset:16
	ds_read_b128 v[40:43], v130 offset:512
	ds_read_b128 v[36:39], v130 offset:528
	ds_read_b128 v[32:35], v130 offset:1024
	ds_read_b128 v[28:31], v130 offset:1040
	ds_read_b128 v[24:27], v130 offset:1536
	ds_read_b128 v[20:23], v130 offset:1552
	s_and_saveexec_b64 s[62:63], s[16:17]
	s_cbranch_execz .LBB0_562
	s_waitcnt lgkmcnt(6)
	v_pk_add_f32 v[68:69], v[54:55], 0 op_sel_hi:[1,0]
	v_pk_add_f32 v[70:71], v[52:53], 0 op_sel_hi:[1,0]
	s_waitcnt lgkmcnt(4)
	v_pk_add_f32 v[68:69], v[68:69], v[38:39]
	v_pk_add_f32 v[70:71], v[70:71], v[36:37]
	s_waitcnt lgkmcnt(2)
	v_pk_add_f32 v[68:69], v[68:69], v[30:31]
	v_pk_add_f32 v[70:71], v[70:71], v[28:29]
	s_waitcnt lgkmcnt(0)
	v_pk_add_f32 v[74:75], v[68:69], v[22:23]
	v_pk_add_f32 v[72:73], v[70:71], v[20:21]
	v_pk_add_f32 v[68:69], v[58:59], 0 op_sel_hi:[1,0]
	v_pk_add_f32 v[70:71], v[56:57], 0 op_sel_hi:[1,0]
	v_pk_add_f32 v[68:69], v[68:69], v[42:43]
	v_pk_add_f32 v[70:71], v[70:71], v[40:41]
	v_pk_add_f32 v[68:69], v[68:69], v[34:35]
	v_pk_add_f32 v[70:71], v[70:71], v[32:33]
	v_pk_add_f32 v[76:77], v[68:69], v[26:27]
	v_pk_add_f32 v[68:69], v[70:71], v[24:25]
	s_nop 0
	v_mul_f32_e32 v2, 0x3fb8aa3b, v68
	v_exp_f32_e32 v68, v2
	v_mul_f32_e32 v2, 0x3fb8aa3b, v69
	v_exp_f32_e32 v69, v2
	v_mul_f32_e32 v2, 0x3fb8aa3b, v76
	v_exp_f32_e32 v70, v2
	v_mul_f32_e32 v2, 0x3fb8aa3b, v77
	v_exp_f32_e32 v71, v2
	v_mul_f32_e32 v2, 0x3fb8aa3b, v72
	v_exp_f32_e32 v72, v2
	v_mul_f32_e32 v2, 0x3fb8aa3b, v73
	v_exp_f32_e32 v73, v2
	v_mul_f32_e32 v2, 0x3fb8aa3b, v74
	v_exp_f32_e32 v74, v2
	v_mul_f32_e32 v2, 0x3fb8aa3b, v75
	v_exp_f32_e32 v75, v2
	global_store_dwordx4 v[66:67], v[68:71], off
	global_store_dwordx4 v[64:65], v[72:75], off

; #define GRID_SYNC_CG() do { grid.sync(); GRID_SYNC(); } while (0)
; __global__ void __launch_bounds__(NTHREADS, 2) fwd_megakernel(Args a) {
;     ...
;     GRID_SYNC_CG();
.LBB0_1087:
	s_branch .Lskip_cgsync
	v_lshrrev_b32_e32 v2, 20, v0
	v_lshrrev_b32_e32 v0, 10, v0
	v_or_b32_e32 v0, v0, v2
	s_movk_i32 s0, 0x3ff
	v_and_or_b32 v0, v0, s0, v1
	v_cmp_eq_u32_e32 vcc, 0, v0
	s_waitcnt lgkmcnt(0)
	s_barrier
	s_and_saveexec_b64 s[4:5], vcc
	s_cbranch_execz .LBB0_1097
	v_readlane_b32 s0, v251, 4
	v_readlane_b32 s1, v251, 5
	buffer_wbl2 sc1
	s_waitcnt vmcnt(0)
	s_load_dwordx2 s[6:7], s[0:1], 0x58
	v_mov_b32_e32 v2, 0
	s_mov_b64 s[10:11], exec
	v_mbcnt_lo_u32_b32 v1, s10, 0
	v_mbcnt_hi_u32_b32 v1, s11, v1
	s_waitcnt lgkmcnt(0)
	global_load_dword v0, v2, s[6:7] offset:40
	v_cmp_eq_u32_e32 vcc, 0, v1
	s_and_saveexec_b64 s[12:13], vcc
	s_cbranch_execz .LBB0_1090
	s_bcnt1_i32_b64 s0, s[10:11]
	v_mov_b32_e32 v3, s0
	global_atomic_add v3, v2, v3, s[6:7] offset:32 sc0

; __device__ __forceinline__ unsigned xb_ld(unsigned* p)              { return __hip_atomic_load(p, __ATOMIC_RELAXED, __HIP_MEMORY_SCOPE_AGENT); }
; __device__ __forceinline__ void xcd_barrier_complete(unsigned* bar, unsigned x, unsigned& nloc, unsigned& nx) {
;     const unsigned G = gridDim.x * gridDim.y * gridDim.z;
;     unsigned sum, cnt, mine, sp = 0u;
;     for (;;) {
;         sum = 0u; cnt = 0u; mine = 0u;
; #pragma unroll
;         for (unsigned j = 0; j < 16; ++j) { const unsigned c = xb_ld(&bar[XB_XCNT(j)]); sum += c; cnt += (c > 0u) ? 1u : 0u; mine = (j == x) ? c : mine; }
; __device__ __forceinline__ void xcd_barrier(const XcdBarrier& b, const bool leader) {
;     asm volatile("s_waitcnt vmcnt(0)" ::: "memory");
;     __syncthreads();
;     if (leader) {
;         unsigned* bar = b.bar;
;         __builtin_amdgcn_s_waitcnt(0);
;         unsigned nloc = b.st[0], nx = b.st[1];
;         if (nloc == 0u) { xcd_barrier_complete(bar, b.x, nloc, nx); b.st[0] = nloc; b.st[1] = nx; }
.Lskip_cgsync:
	s_getreg_b32 s0, hwreg(HW_REG_XCC_ID, 0, 4)
	s_waitcnt vmcnt(0)
	s_barrier
	s_mov_b64 s[4:5], exec
	v_readlane_b32 s2, v251, 6
	v_readlane_b32 s3, v251, 7
	s_and_b64 s[2:3], s[4:5], s[2:3]
	s_mov_b64 exec, s[2:3]
	s_cbranch_execz .LBB0_1149
	s_add_i32 s1, 0, 0x22000
	v_mov_b32_e32 v0, s1
	s_waitcnt vmcnt(0) expcnt(0) lgkmcnt(0)
	ds_read_b32 v2, v0
	s_add_i32 s1, 0, 0x22004
	v_mov_b32_e32 v0, s1
	ds_read_b32 v0, v0
	s_and_b32 s0, s0, 15
	s_waitcnt lgkmcnt(1)
	v_cmp_ne_u32_e32 vcc, 0, v2
	s_cbranch_vccnz .LBB0_1113
	s_add_u32 s6, s18, 0x1d798200
	s_addc_u32 s7, s19, 0
	s_add_u32 s10, s18, 0x1d798400
	s_addc_u32 s11, s19, 0
	s_add_u32 s12, s18, 0x1d798500
	s_addc_u32 s13, s19, 0
	s_add_u32 s14, s18, 0x1d798600
	s_addc_u32 s15, s19, 0
	s_add_u32 s16, s18, 0x1d798700
	s_addc_u32 s17, s19, 0
	s_add_u32 s20, s18, 0x1d798800
	s_addc_u32 s21, s19, 0
	s_add_u32 s22, s18, 0x1d798900
	s_addc_u32 s23, s19, 0
	s_add_u32 s24, s18, 0x1d798a00
	s_addc_u32 s25, s19, 0
	s_add_u32 s26, s18, 0x1d798b00
	s_addc_u32 s27, s19, 0
	s_add_u32 s28, s18, 0x1d798c00
	s_addc_u32 s29, s19, 0
	s_add_u32 s30, s18, 0x1d798d00
	s_addc_u32 s31, s19, 0
	s_add_u32 s34, s18, 0x1d798e00
	s_addc_u32 s35, s19, 0
	s_add_u32 s36, s18, 0x1d798f00
	s_addc_u32 s37, s19, 0
	s_add_u32 s38, s18, 0x1d799000
	s_addc_u32 s39, s19, 0
	s_add_u32 s40, s18, 0x1d799100
	s_addc_u32 s41, s19, 0
	s_add_u32 s42, s18, 0x1d799200
	s_addc_u32 s43, s19, 0
	s_add_u32 s44, s18, 0x1d799300
	s_addc_u32 s45, s19, 0
	s_mov_b32 s1, 1
	v_mov_b32_e32 v16, 0
	s_branch .LBB0_1101
